# s5_pass1 scan: B.u on the f32 matrix core as well (4 blocks of 32 steps per task)
# speedup vs baseline: 1.0050x; 1.0046x over previous
; __device__ __forceinline__ void s5_pass1(const Params& p, int layer, int task, char* sm) {
;     ...
; #pragma unroll
;   for (int h = 0; h < 16; h++) { B2[h].x = p.SB[pi * 32 + h]; B2[h].y = p.SB[pi * 32 + 16 + h]; }
;   const float ar = p.SA[pi * 4], ai = p.SA[pi * 4 + 1];
;   float sr = 0.f, si = 0.f;
;   __builtin_amdgcn_wave_barrier();
;   for (int l = 0; l < 128; l++) S5_STEP(sU + l * 16)
.LBB0_477:
	v_mov_b32_e32 v37, v38
	s_nop 1
	v_permlane32_swap_b32_e32 v16, v12
	v_permlane32_swap_b32_e32 v17, v13
	v_permlane32_swap_b32_e32 v18, v14
	v_permlane32_swap_b32_e32 v19, v15
	v_permlane32_swap_b32_e32 v20, v8
	v_permlane32_swap_b32_e32 v21, v9
	v_permlane32_swap_b32_e32 v22, v10
	v_permlane32_swap_b32_e32 v23, v11
	v_permlane32_swap_b32_e32 v24, v4
	v_permlane32_swap_b32_e32 v25, v5
	v_permlane32_swap_b32_e32 v26, v6
	v_permlane32_swap_b32_e32 v27, v7
	v_permlane32_swap_b32_e32 v28, v0
	v_permlane32_swap_b32_e32 v29, v1
	v_permlane32_swap_b32_e32 v30, v2
	v_permlane32_swap_b32_e32 v31, v3
	v_and_b32_e32 v186, 31, v202
	v_lshrrev_b32_e32 v187, 5, v202
	v_lshlrev_b32_e32 v186, 6, v186
	v_lshl_add_u32 v186, v187, 2, v186
	v_add_u32_e32 v186, v41, v186
	ds_read2_b32 v[178:179], v186 offset0:0 offset1:2
	ds_read2_b32 v[180:181], v186 offset0:4 offset1:6
	ds_read2_b32 v[182:183], v186 offset0:8 offset1:10
	ds_read2_b32 v[184:185], v186 offset0:12 offset1:14
	s_waitcnt lgkmcnt(0)
	v_add_u32_e32 v186, 0x800, v186
	v_mfma_f32_32x32x2_f32 v[108:123], v178, v16, 0
	v_mfma_f32_32x32x2_f32 v[124:139], v178, v17, 0
	v_mfma_f32_32x32x2_f32 v[146:161], v178, v12, 0
	v_mfma_f32_32x32x2_f32 v[162:177], v178, v13, 0
	v_mfma_f32_32x32x2_f32 v[108:123], v179, v18, v[108:123]
	v_mfma_f32_32x32x2_f32 v[124:139], v179, v19, v[124:139]
	v_mfma_f32_32x32x2_f32 v[146:161], v179, v14, v[146:161]
	v_mfma_f32_32x32x2_f32 v[162:177], v179, v15, v[162:177]
	v_mfma_f32_32x32x2_f32 v[108:123], v180, v20, v[108:123]
	v_mfma_f32_32x32x2_f32 v[124:139], v180, v21, v[124:139]
	v_mfma_f32_32x32x2_f32 v[146:161], v180, v8, v[146:161]
	v_mfma_f32_32x32x2_f32 v[162:177], v180, v9, v[162:177]
	v_mfma_f32_32x32x2_f32 v[108:123], v181, v22, v[108:123]
	v_mfma_f32_32x32x2_f32 v[124:139], v181, v23, v[124:139]
	v_mfma_f32_32x32x2_f32 v[146:161], v181, v10, v[146:161]
	v_mfma_f32_32x32x2_f32 v[162:177], v181, v11, v[162:177]
	v_mfma_f32_32x32x2_f32 v[108:123], v182, v24, v[108:123]
	v_mfma_f32_32x32x2_f32 v[124:139], v182, v25, v[124:139]
	v_mfma_f32_32x32x2_f32 v[146:161], v182, v4, v[146:161]
	v_mfma_f32_32x32x2_f32 v[162:177], v182, v5, v[162:177]
	v_mfma_f32_32x32x2_f32 v[108:123], v183, v26, v[108:123]
	v_mfma_f32_32x32x2_f32 v[124:139], v183, v27, v[124:139]
	v_mfma_f32_32x32x2_f32 v[146:161], v183, v6, v[146:161]
	v_mfma_f32_32x32x2_f32 v[162:177], v183, v7, v[162:177]
	v_mfma_f32_32x32x2_f32 v[108:123], v184, v28, v[108:123]
	v_mfma_f32_32x32x2_f32 v[124:139], v184, v29, v[124:139]
	v_mfma_f32_32x32x2_f32 v[146:161], v184, v0, v[146:161]
	v_mfma_f32_32x32x2_f32 v[162:177], v184, v1, v[162:177]
	v_mfma_f32_32x32x2_f32 v[108:123], v185, v30, v[108:123]
	v_mfma_f32_32x32x2_f32 v[124:139], v185, v31, v[124:139]
	v_mfma_f32_32x32x2_f32 v[146:161], v185, v2, v[146:161]
	v_mfma_f32_32x32x2_f32 v[162:177], v185, v3, v[162:177]
	s_nop 7
	s_nop 7
	s_nop 7
	v_permlane32_swap_b32_e32 v108, v146
	v_permlane32_swap_b32_e32 v124, v162
	v_permlane32_swap_b32_e32 v109, v147
	v_permlane32_swap_b32_e32 v125, v163
	v_permlane32_swap_b32_e32 v110, v148
	v_permlane32_swap_b32_e32 v126, v164
	v_permlane32_swap_b32_e32 v111, v149
	v_permlane32_swap_b32_e32 v127, v165
	v_permlane32_swap_b32_e32 v112, v150
	v_permlane32_swap_b32_e32 v128, v166
	v_permlane32_swap_b32_e32 v113, v151
	v_permlane32_swap_b32_e32 v129, v167
	v_permlane32_swap_b32_e32 v114, v152
	v_permlane32_swap_b32_e32 v130, v168
	v_permlane32_swap_b32_e32 v115, v153
	v_permlane32_swap_b32_e32 v131, v169
	v_permlane32_swap_b32_e32 v116, v154
	v_permlane32_swap_b32_e32 v132, v170
	v_permlane32_swap_b32_e32 v117, v155
	v_permlane32_swap_b32_e32 v133, v171
	v_permlane32_swap_b32_e32 v118, v156
	v_permlane32_swap_b32_e32 v134, v172
	v_permlane32_swap_b32_e32 v119, v157
	v_permlane32_swap_b32_e32 v135, v173
	v_permlane32_swap_b32_e32 v120, v158
	v_permlane32_swap_b32_e32 v136, v174
	v_permlane32_swap_b32_e32 v121, v159
	v_permlane32_swap_b32_e32 v137, v175
	v_permlane32_swap_b32_e32 v122, v160
	v_permlane32_swap_b32_e32 v138, v176
	v_permlane32_swap_b32_e32 v123, v161
	v_permlane32_swap_b32_e32 v139, v177
	v_pk_mul_f32 v[188:189], v[34:35], v[36:37] op_sel:[0,1]
	s_nop 0
	v_pk_fma_f32 v[190:191], v[32:33], v[36:37], v[188:189] op_sel_hi:[1,0,1] neg_lo:[0,0,1]
	s_nop 0
	v_add_f32_e32 v36, v190, v108
	v_add_f32_e32 v37, v191, v124
	v_pk_mul_f32 v[188:189], v[34:35], v[36:37] op_sel:[0,1]
	s_nop 0
	v_pk_fma_f32 v[190:191], v[32:33], v[36:37], v[188:189] op_sel_hi:[1,0,1] neg_lo:[0,0,1]
	s_nop 0
	v_add_f32_e32 v36, v190, v109
	v_add_f32_e32 v37, v191, v125
	v_pk_mul_f32 v[188:189], v[34:35], v[36:37] op_sel:[0,1]
	s_nop 0
	v_pk_fma_f32 v[190:191], v[32:33], v[36:37], v[188:189] op_sel_hi:[1,0,1] neg_lo:[0,0,1]
	s_nop 0
	v_add_f32_e32 v36, v190, v110
	v_add_f32_e32 v37, v191, v126
	v_pk_mul_f32 v[188:189], v[34:35], v[36:37] op_sel:[0,1]
	s_nop 0
	v_pk_fma_f32 v[190:191], v[32:33], v[36:37], v[188:189] op_sel_hi:[1,0,1] neg_lo:[0,0,1]
	s_nop 0
	v_add_f32_e32 v36, v190, v111
	v_add_f32_e32 v37, v191, v127
	v_pk_mul_f32 v[188:189], v[34:35], v[36:37] op_sel:[0,1]
	s_nop 0
	v_pk_fma_f32 v[190:191], v[32:33], v[36:37], v[188:189] op_sel_hi:[1,0,1] neg_lo:[0,0,1]
	s_nop 0
	v_add_f32_e32 v36, v190, v146
	v_add_f32_e32 v37, v191, v162
	v_pk_mul_f32 v[188:189], v[34:35], v[36:37] op_sel:[0,1]
	s_nop 0
	v_pk_fma_f32 v[190:191], v[32:33], v[36:37], v[188:189] op_sel_hi:[1,0,1] neg_lo:[0,0,1]
	s_nop 0
	v_add_f32_e32 v36, v190, v147
	v_add_f32_e32 v37, v191, v163
	v_pk_mul_f32 v[188:189], v[34:35], v[36:37] op_sel:[0,1]
	s_nop 0
	v_pk_fma_f32 v[190:191], v[32:33], v[36:37], v[188:189] op_sel_hi:[1,0,1] neg_lo:[0,0,1]
	s_nop 0
	v_add_f32_e32 v36, v190, v148
; __device__ __forceinline__ void s5_pass1(const Params& p, int layer, int task, char* sm) {
;     ...
;   for (int l = 0; l < 128; l++) S5_STEP(sU + l * 16)
	v_add_f32_e32 v37, v191, v164
	v_pk_mul_f32 v[188:189], v[34:35], v[36:37] op_sel:[0,1]
	s_nop 0
	v_pk_fma_f32 v[190:191], v[32:33], v[36:37], v[188:189] op_sel_hi:[1,0,1] neg_lo:[0,0,1]
	s_nop 0
	v_add_f32_e32 v36, v190, v149
	v_add_f32_e32 v37, v191, v165
	v_pk_mul_f32 v[188:189], v[34:35], v[36:37] op_sel:[0,1]
	s_nop 0
	v_pk_fma_f32 v[190:191], v[32:33], v[36:37], v[188:189] op_sel_hi:[1,0,1] neg_lo:[0,0,1]
	s_nop 0
	v_add_f32_e32 v36, v190, v112
	v_add_f32_e32 v37, v191, v128
	v_pk_mul_f32 v[188:189], v[34:35], v[36:37] op_sel:[0,1]
	s_nop 0
	v_pk_fma_f32 v[190:191], v[32:33], v[36:37], v[188:189] op_sel_hi:[1,0,1] neg_lo:[0,0,1]
	s_nop 0
	v_add_f32_e32 v36, v190, v113
	v_add_f32_e32 v37, v191, v129
	v_pk_mul_f32 v[188:189], v[34:35], v[36:37] op_sel:[0,1]
	s_nop 0
	v_pk_fma_f32 v[190:191], v[32:33], v[36:37], v[188:189] op_sel_hi:[1,0,1] neg_lo:[0,0,1]
	s_nop 0
	v_add_f32_e32 v36, v190, v114
	v_add_f32_e32 v37, v191, v130
	v_pk_mul_f32 v[188:189], v[34:35], v[36:37] op_sel:[0,1]
	s_nop 0
	v_pk_fma_f32 v[190:191], v[32:33], v[36:37], v[188:189] op_sel_hi:[1,0,1] neg_lo:[0,0,1]
	s_nop 0
	v_add_f32_e32 v36, v190, v115
	v_add_f32_e32 v37, v191, v131
	v_pk_mul_f32 v[188:189], v[34:35], v[36:37] op_sel:[0,1]
	s_nop 0
	v_pk_fma_f32 v[190:191], v[32:33], v[36:37], v[188:189] op_sel_hi:[1,0,1] neg_lo:[0,0,1]
	s_nop 0
	v_add_f32_e32 v36, v190, v150
	v_add_f32_e32 v37, v191, v166
	v_pk_mul_f32 v[188:189], v[34:35], v[36:37] op_sel:[0,1]
	s_nop 0
	v_pk_fma_f32 v[190:191], v[32:33], v[36:37], v[188:189] op_sel_hi:[1,0,1] neg_lo:[0,0,1]
	s_nop 0
	v_add_f32_e32 v36, v190, v151
	v_add_f32_e32 v37, v191, v167
	v_pk_mul_f32 v[188:189], v[34:35], v[36:37] op_sel:[0,1]
	s_nop 0
	v_pk_fma_f32 v[190:191], v[32:33], v[36:37], v[188:189] op_sel_hi:[1,0,1] neg_lo:[0,0,1]
	s_nop 0
	v_add_f32_e32 v36, v190, v152
	v_add_f32_e32 v37, v191, v168
	v_pk_mul_f32 v[188:189], v[34:35], v[36:37] op_sel:[0,1]
	s_nop 0
	v_pk_fma_f32 v[190:191], v[32:33], v[36:37], v[188:189] op_sel_hi:[1,0,1] neg_lo:[0,0,1]
	s_nop 0
	v_add_f32_e32 v36, v190, v153
	v_add_f32_e32 v37, v191, v169
	v_pk_mul_f32 v[188:189], v[34:35], v[36:37] op_sel:[0,1]
	s_nop 0
	v_pk_fma_f32 v[190:191], v[32:33], v[36:37], v[188:189] op_sel_hi:[1,0,1] neg_lo:[0,0,1]
	s_nop 0
	v_add_f32_e32 v36, v190, v116
	v_add_f32_e32 v37, v191, v132
	v_pk_mul_f32 v[188:189], v[34:35], v[36:37] op_sel:[0,1]
	s_nop 0
	v_pk_fma_f32 v[190:191], v[32:33], v[36:37], v[188:189] op_sel_hi:[1,0,1] neg_lo:[0,0,1]
	s_nop 0
	v_add_f32_e32 v36, v190, v117
	v_add_f32_e32 v37, v191, v133
	v_pk_mul_f32 v[188:189], v[34:35], v[36:37] op_sel:[0,1]
	s_nop 0
	v_pk_fma_f32 v[190:191], v[32:33], v[36:37], v[188:189] op_sel_hi:[1,0,1] neg_lo:[0,0,1]
	s_nop 0
	v_add_f32_e32 v36, v190, v118
	v_add_f32_e32 v37, v191, v134
	v_pk_mul_f32 v[188:189], v[34:35], v[36:37] op_sel:[0,1]
	s_nop 0
	v_pk_fma_f32 v[190:191], v[32:33], v[36:37], v[188:189] op_sel_hi:[1,0,1] neg_lo:[0,0,1]
	s_nop 0
	v_add_f32_e32 v36, v190, v119
	v_add_f32_e32 v37, v191, v135
	v_pk_mul_f32 v[188:189], v[34:35], v[36:37] op_sel:[0,1]
	s_nop 0
	v_pk_fma_f32 v[190:191], v[32:33], v[36:37], v[188:189] op_sel_hi:[1,0,1] neg_lo:[0,0,1]
	s_nop 0
	v_add_f32_e32 v36, v190, v154
	v_add_f32_e32 v37, v191, v170
	v_pk_mul_f32 v[188:189], v[34:35], v[36:37] op_sel:[0,1]
	s_nop 0
	v_pk_fma_f32 v[190:191], v[32:33], v[36:37], v[188:189] op_sel_hi:[1,0,1] neg_lo:[0,0,1]
	s_nop 0
	v_add_f32_e32 v36, v190, v155
	v_add_f32_e32 v37, v191, v171
	v_pk_mul_f32 v[188:189], v[34:35], v[36:37] op_sel:[0,1]
	s_nop 0
	v_pk_fma_f32 v[190:191], v[32:33], v[36:37], v[188:189] op_sel_hi:[1,0,1] neg_lo:[0,0,1]
	s_nop 0
	v_add_f32_e32 v36, v190, v156
	v_add_f32_e32 v37, v191, v172
	v_pk_mul_f32 v[188:189], v[34:35], v[36:37] op_sel:[0,1]
	s_nop 0
	v_pk_fma_f32 v[190:191], v[32:33], v[36:37], v[188:189] op_sel_hi:[1,0,1] neg_lo:[0,0,1]
	s_nop 0
	v_add_f32_e32 v36, v190, v157
	v_add_f32_e32 v37, v191, v173
	v_pk_mul_f32 v[188:189], v[34:35], v[36:37] op_sel:[0,1]
	s_nop 0
	v_pk_fma_f32 v[190:191], v[32:33], v[36:37], v[188:189] op_sel_hi:[1,0,1] neg_lo:[0,0,1]
	s_nop 0
	v_add_f32_e32 v36, v190, v120
	v_add_f32_e32 v37, v191, v136
	v_pk_mul_f32 v[188:189], v[34:35], v[36:37] op_sel:[0,1]
	s_nop 0
	v_pk_fma_f32 v[190:191], v[32:33], v[36:37], v[188:189] op_sel_hi:[1,0,1] neg_lo:[0,0,1]
	s_nop 0
	v_add_f32_e32 v36, v190, v121
	v_add_f32_e32 v37, v191, v137
	v_pk_mul_f32 v[188:189], v[34:35], v[36:37] op_sel:[0,1]
	s_nop 0
	v_pk_fma_f32 v[190:191], v[32:33], v[36:37], v[188:189] op_sel_hi:[1,0,1] neg_lo:[0,0,1]
	s_nop 0
	v_add_f32_e32 v36, v190, v122
	v_add_f32_e32 v37, v191, v138
	v_pk_mul_f32 v[188:189], v[34:35], v[36:37] op_sel:[0,1]
	s_nop 0
	v_pk_fma_f32 v[190:191], v[32:33], v[36:37], v[188:189] op_sel_hi:[1,0,1] neg_lo:[0,0,1]
	s_nop 0
	v_add_f32_e32 v36, v190, v123
	v_add_f32_e32 v37, v191, v139
	v_pk_mul_f32 v[188:189], v[34:35], v[36:37] op_sel:[0,1]
	s_nop 0
	v_pk_fma_f32 v[190:191], v[32:33], v[36:37], v[188:189] op_sel_hi:[1,0,1] neg_lo:[0,0,1]
	s_nop 0
	v_add_f32_e32 v36, v190, v158
	v_add_f32_e32 v37, v191, v174
	v_pk_mul_f32 v[188:189], v[34:35], v[36:37] op_sel:[0,1]
	s_nop 0
	v_pk_fma_f32 v[190:191], v[32:33], v[36:37], v[188:189] op_sel_hi:[1,0,1] neg_lo:[0,0,1]
	s_nop 0
	v_add_f32_e32 v36, v190, v159
	v_add_f32_e32 v37, v191, v175
	v_pk_mul_f32 v[188:189], v[34:35], v[36:37] op_sel:[0,1]
	s_nop 0
	v_pk_fma_f32 v[190:191], v[32:33], v[36:37], v[188:189] op_sel_hi:[1,0,1] neg_lo:[0,0,1]
	s_nop 0
	v_add_f32_e32 v36, v190, v160
	v_add_f32_e32 v37, v191, v176
	v_pk_mul_f32 v[188:189], v[34:35], v[36:37] op_sel:[0,1]
	s_nop 0
	v_pk_fma_f32 v[190:191], v[32:33], v[36:37], v[188:189] op_sel_hi:[1,0,1] neg_lo:[0,0,1]
	s_nop 0
	v_add_f32_e32 v36, v190, v161
	v_add_f32_e32 v37, v191, v177
	ds_read2_b32 v[178:179], v186 offset0:0 offset1:2
	ds_read2_b32 v[180:181], v186 offset0:4 offset1:6
	ds_read2_b32 v[182:183], v186 offset0:8 offset1:10
	ds_read2_b32 v[184:185], v186 offset0:12 offset1:14
	s_waitcnt lgkmcnt(0)
; __device__ __forceinline__ void s5_pass1(const Params& p, int layer, int task, char* sm) {
;     ...
; #pragma unroll
;   for (int h = 0; h < 16; h++) { B2[h].x = p.SB[pi * 32 + h]; B2[h].y = p.SB[pi * 32 + 16 + h]; }
;   const float ar = p.SA[pi * 4], ai = p.SA[pi * 4 + 1];
;   float sr = 0.f, si = 0.f;
;   __builtin_amdgcn_wave_barrier();
;   for (int l = 0; l < 128; l++) S5_STEP(sU + l * 16)
	v_add_u32_e32 v186, 0x800, v186
	v_mfma_f32_32x32x2_f32 v[108:123], v178, v16, 0
	v_mfma_f32_32x32x2_f32 v[124:139], v178, v17, 0
	v_mfma_f32_32x32x2_f32 v[146:161], v178, v12, 0
	v_mfma_f32_32x32x2_f32 v[162:177], v178, v13, 0
	v_mfma_f32_32x32x2_f32 v[108:123], v179, v18, v[108:123]
	v_mfma_f32_32x32x2_f32 v[124:139], v179, v19, v[124:139]
	v_mfma_f32_32x32x2_f32 v[146:161], v179, v14, v[146:161]
	v_mfma_f32_32x32x2_f32 v[162:177], v179, v15, v[162:177]
	v_mfma_f32_32x32x2_f32 v[108:123], v180, v20, v[108:123]
	v_mfma_f32_32x32x2_f32 v[124:139], v180, v21, v[124:139]
	v_mfma_f32_32x32x2_f32 v[146:161], v180, v8, v[146:161]
	v_mfma_f32_32x32x2_f32 v[162:177], v180, v9, v[162:177]
	v_mfma_f32_32x32x2_f32 v[108:123], v181, v22, v[108:123]
	v_mfma_f32_32x32x2_f32 v[124:139], v181, v23, v[124:139]
	v_mfma_f32_32x32x2_f32 v[146:161], v181, v10, v[146:161]
	v_mfma_f32_32x32x2_f32 v[162:177], v181, v11, v[162:177]
	v_mfma_f32_32x32x2_f32 v[108:123], v182, v24, v[108:123]
	v_mfma_f32_32x32x2_f32 v[124:139], v182, v25, v[124:139]
	v_mfma_f32_32x32x2_f32 v[146:161], v182, v4, v[146:161]
	v_mfma_f32_32x32x2_f32 v[162:177], v182, v5, v[162:177]
	v_mfma_f32_32x32x2_f32 v[108:123], v183, v26, v[108:123]
	v_mfma_f32_32x32x2_f32 v[124:139], v183, v27, v[124:139]
	v_mfma_f32_32x32x2_f32 v[146:161], v183, v6, v[146:161]
	v_mfma_f32_32x32x2_f32 v[162:177], v183, v7, v[162:177]
	v_mfma_f32_32x32x2_f32 v[108:123], v184, v28, v[108:123]
	v_mfma_f32_32x32x2_f32 v[124:139], v184, v29, v[124:139]
	v_mfma_f32_32x32x2_f32 v[146:161], v184, v0, v[146:161]
	v_mfma_f32_32x32x2_f32 v[162:177], v184, v1, v[162:177]
	v_mfma_f32_32x32x2_f32 v[108:123], v185, v30, v[108:123]
	v_mfma_f32_32x32x2_f32 v[124:139], v185, v31, v[124:139]
	v_mfma_f32_32x32x2_f32 v[146:161], v185, v2, v[146:161]
	v_mfma_f32_32x32x2_f32 v[162:177], v185, v3, v[162:177]
	s_nop 7
	s_nop 7
	s_nop 7
	v_permlane32_swap_b32_e32 v108, v146
	v_permlane32_swap_b32_e32 v124, v162
	v_permlane32_swap_b32_e32 v109, v147
	v_permlane32_swap_b32_e32 v125, v163
	v_permlane32_swap_b32_e32 v110, v148
	v_permlane32_swap_b32_e32 v126, v164
	v_permlane32_swap_b32_e32 v111, v149
	v_permlane32_swap_b32_e32 v127, v165
	v_permlane32_swap_b32_e32 v112, v150
	v_permlane32_swap_b32_e32 v128, v166
	v_permlane32_swap_b32_e32 v113, v151
	v_permlane32_swap_b32_e32 v129, v167
	v_permlane32_swap_b32_e32 v114, v152
	v_permlane32_swap_b32_e32 v130, v168
	v_permlane32_swap_b32_e32 v115, v153
	v_permlane32_swap_b32_e32 v131, v169
	v_permlane32_swap_b32_e32 v116, v154
	v_permlane32_swap_b32_e32 v132, v170
	v_permlane32_swap_b32_e32 v117, v155
	v_permlane32_swap_b32_e32 v133, v171
	v_permlane32_swap_b32_e32 v118, v156
	v_permlane32_swap_b32_e32 v134, v172
	v_permlane32_swap_b32_e32 v119, v157
	v_permlane32_swap_b32_e32 v135, v173
	v_permlane32_swap_b32_e32 v120, v158
	v_permlane32_swap_b32_e32 v136, v174
	v_permlane32_swap_b32_e32 v121, v159
	v_permlane32_swap_b32_e32 v137, v175
	v_permlane32_swap_b32_e32 v122, v160
	v_permlane32_swap_b32_e32 v138, v176
	v_permlane32_swap_b32_e32 v123, v161
	v_permlane32_swap_b32_e32 v139, v177
	v_pk_mul_f32 v[188:189], v[34:35], v[36:37] op_sel:[0,1]
	s_nop 0
	v_pk_fma_f32 v[190:191], v[32:33], v[36:37], v[188:189] op_sel_hi:[1,0,1] neg_lo:[0,0,1]
	s_nop 0
	v_add_f32_e32 v36, v190, v108
	v_add_f32_e32 v37, v191, v124
	v_pk_mul_f32 v[188:189], v[34:35], v[36:37] op_sel:[0,1]
	s_nop 0
	v_pk_fma_f32 v[190:191], v[32:33], v[36:37], v[188:189] op_sel_hi:[1,0,1] neg_lo:[0,0,1]
	s_nop 0
	v_add_f32_e32 v36, v190, v109
	v_add_f32_e32 v37, v191, v125
	v_pk_mul_f32 v[188:189], v[34:35], v[36:37] op_sel:[0,1]
	s_nop 0
	v_pk_fma_f32 v[190:191], v[32:33], v[36:37], v[188:189] op_sel_hi:[1,0,1] neg_lo:[0,0,1]
	s_nop 0
	v_add_f32_e32 v36, v190, v110
	v_add_f32_e32 v37, v191, v126
	v_pk_mul_f32 v[188:189], v[34:35], v[36:37] op_sel:[0,1]
	s_nop 0
	v_pk_fma_f32 v[190:191], v[32:33], v[36:37], v[188:189] op_sel_hi:[1,0,1] neg_lo:[0,0,1]
	s_nop 0
	v_add_f32_e32 v36, v190, v111
	v_add_f32_e32 v37, v191, v127
	v_pk_mul_f32 v[188:189], v[34:35], v[36:37] op_sel:[0,1]
	s_nop 0
	v_pk_fma_f32 v[190:191], v[32:33], v[36:37], v[188:189] op_sel_hi:[1,0,1] neg_lo:[0,0,1]
	s_nop 0
	v_add_f32_e32 v36, v190, v146
	v_add_f32_e32 v37, v191, v162
	v_pk_mul_f32 v[188:189], v[34:35], v[36:37] op_sel:[0,1]
	s_nop 0
	v_pk_fma_f32 v[190:191], v[32:33], v[36:37], v[188:189] op_sel_hi:[1,0,1] neg_lo:[0,0,1]
	s_nop 0
	v_add_f32_e32 v36, v190, v147
	v_add_f32_e32 v37, v191, v163
	v_pk_mul_f32 v[188:189], v[34:35], v[36:37] op_sel:[0,1]
	s_nop 0
	v_pk_fma_f32 v[190:191], v[32:33], v[36:37], v[188:189] op_sel_hi:[1,0,1] neg_lo:[0,0,1]
	s_nop 0
	v_add_f32_e32 v36, v190, v148
	v_add_f32_e32 v37, v191, v164
	v_pk_mul_f32 v[188:189], v[34:35], v[36:37] op_sel:[0,1]
	s_nop 0
	v_pk_fma_f32 v[190:191], v[32:33], v[36:37], v[188:189] op_sel_hi:[1,0,1] neg_lo:[0,0,1]
	s_nop 0
	v_add_f32_e32 v36, v190, v149
	v_add_f32_e32 v37, v191, v165
	v_pk_mul_f32 v[188:189], v[34:35], v[36:37] op_sel:[0,1]
	s_nop 0
	v_pk_fma_f32 v[190:191], v[32:33], v[36:37], v[188:189] op_sel_hi:[1,0,1] neg_lo:[0,0,1]
	s_nop 0
	v_add_f32_e32 v36, v190, v112
	v_add_f32_e32 v37, v191, v128
	v_pk_mul_f32 v[188:189], v[34:35], v[36:37] op_sel:[0,1]
	s_nop 0
	v_pk_fma_f32 v[190:191], v[32:33], v[36:37], v[188:189] op_sel_hi:[1,0,1] neg_lo:[0,0,1]
	s_nop 0
	v_add_f32_e32 v36, v190, v113
	v_add_f32_e32 v37, v191, v129
	v_pk_mul_f32 v[188:189], v[34:35], v[36:37] op_sel:[0,1]
	s_nop 0
	v_pk_fma_f32 v[190:191], v[32:33], v[36:37], v[188:189] op_sel_hi:[1,0,1] neg_lo:[0,0,1]
	s_nop 0
	v_add_f32_e32 v36, v190, v114
	v_add_f32_e32 v37, v191, v130
	v_pk_mul_f32 v[188:189], v[34:35], v[36:37] op_sel:[0,1]
; __device__ __forceinline__ void s5_pass1(const Params& p, int layer, int task, char* sm) {
;     ...
;   for (int l = 0; l < 128; l++) S5_STEP(sU + l * 16)
	s_nop 0
	v_pk_fma_f32 v[190:191], v[32:33], v[36:37], v[188:189] op_sel_hi:[1,0,1] neg_lo:[0,0,1]
	s_nop 0
	v_add_f32_e32 v36, v190, v115
	v_add_f32_e32 v37, v191, v131
	v_pk_mul_f32 v[188:189], v[34:35], v[36:37] op_sel:[0,1]
	s_nop 0
	v_pk_fma_f32 v[190:191], v[32:33], v[36:37], v[188:189] op_sel_hi:[1,0,1] neg_lo:[0,0,1]
	s_nop 0
	v_add_f32_e32 v36, v190, v150
	v_add_f32_e32 v37, v191, v166
	v_pk_mul_f32 v[188:189], v[34:35], v[36:37] op_sel:[0,1]
	s_nop 0
	v_pk_fma_f32 v[190:191], v[32:33], v[36:37], v[188:189] op_sel_hi:[1,0,1] neg_lo:[0,0,1]
	s_nop 0
	v_add_f32_e32 v36, v190, v151
	v_add_f32_e32 v37, v191, v167
	v_pk_mul_f32 v[188:189], v[34:35], v[36:37] op_sel:[0,1]
	s_nop 0
	v_pk_fma_f32 v[190:191], v[32:33], v[36:37], v[188:189] op_sel_hi:[1,0,1] neg_lo:[0,0,1]
	s_nop 0
	v_add_f32_e32 v36, v190, v152
	v_add_f32_e32 v37, v191, v168
	v_pk_mul_f32 v[188:189], v[34:35], v[36:37] op_sel:[0,1]
	s_nop 0
	v_pk_fma_f32 v[190:191], v[32:33], v[36:37], v[188:189] op_sel_hi:[1,0,1] neg_lo:[0,0,1]
	s_nop 0
	v_add_f32_e32 v36, v190, v153
	v_add_f32_e32 v37, v191, v169
	v_pk_mul_f32 v[188:189], v[34:35], v[36:37] op_sel:[0,1]
	s_nop 0
	v_pk_fma_f32 v[190:191], v[32:33], v[36:37], v[188:189] op_sel_hi:[1,0,1] neg_lo:[0,0,1]
	s_nop 0
	v_add_f32_e32 v36, v190, v116
	v_add_f32_e32 v37, v191, v132
	v_pk_mul_f32 v[188:189], v[34:35], v[36:37] op_sel:[0,1]
	s_nop 0
	v_pk_fma_f32 v[190:191], v[32:33], v[36:37], v[188:189] op_sel_hi:[1,0,1] neg_lo:[0,0,1]
	s_nop 0
	v_add_f32_e32 v36, v190, v117
	v_add_f32_e32 v37, v191, v133
	v_pk_mul_f32 v[188:189], v[34:35], v[36:37] op_sel:[0,1]
	s_nop 0
	v_pk_fma_f32 v[190:191], v[32:33], v[36:37], v[188:189] op_sel_hi:[1,0,1] neg_lo:[0,0,1]
	s_nop 0
	v_add_f32_e32 v36, v190, v118
	v_add_f32_e32 v37, v191, v134
	v_pk_mul_f32 v[188:189], v[34:35], v[36:37] op_sel:[0,1]
	s_nop 0
	v_pk_fma_f32 v[190:191], v[32:33], v[36:37], v[188:189] op_sel_hi:[1,0,1] neg_lo:[0,0,1]
	s_nop 0
	v_add_f32_e32 v36, v190, v119
	v_add_f32_e32 v37, v191, v135
	v_pk_mul_f32 v[188:189], v[34:35], v[36:37] op_sel:[0,1]
	s_nop 0
	v_pk_fma_f32 v[190:191], v[32:33], v[36:37], v[188:189] op_sel_hi:[1,0,1] neg_lo:[0,0,1]
	s_nop 0
	v_add_f32_e32 v36, v190, v154
	v_add_f32_e32 v37, v191, v170
	v_pk_mul_f32 v[188:189], v[34:35], v[36:37] op_sel:[0,1]
	s_nop 0
	v_pk_fma_f32 v[190:191], v[32:33], v[36:37], v[188:189] op_sel_hi:[1,0,1] neg_lo:[0,0,1]
	s_nop 0
	v_add_f32_e32 v36, v190, v155
	v_add_f32_e32 v37, v191, v171
	v_pk_mul_f32 v[188:189], v[34:35], v[36:37] op_sel:[0,1]
	s_nop 0
	v_pk_fma_f32 v[190:191], v[32:33], v[36:37], v[188:189] op_sel_hi:[1,0,1] neg_lo:[0,0,1]
	s_nop 0
	v_add_f32_e32 v36, v190, v156
	v_add_f32_e32 v37, v191, v172
	v_pk_mul_f32 v[188:189], v[34:35], v[36:37] op_sel:[0,1]
	s_nop 0
	v_pk_fma_f32 v[190:191], v[32:33], v[36:37], v[188:189] op_sel_hi:[1,0,1] neg_lo:[0,0,1]
	s_nop 0
	v_add_f32_e32 v36, v190, v157
	v_add_f32_e32 v37, v191, v173
	v_pk_mul_f32 v[188:189], v[34:35], v[36:37] op_sel:[0,1]
	s_nop 0
	v_pk_fma_f32 v[190:191], v[32:33], v[36:37], v[188:189] op_sel_hi:[1,0,1] neg_lo:[0,0,1]
	s_nop 0
	v_add_f32_e32 v36, v190, v120
	v_add_f32_e32 v37, v191, v136
	v_pk_mul_f32 v[188:189], v[34:35], v[36:37] op_sel:[0,1]
	s_nop 0
	v_pk_fma_f32 v[190:191], v[32:33], v[36:37], v[188:189] op_sel_hi:[1,0,1] neg_lo:[0,0,1]
	s_nop 0
	v_add_f32_e32 v36, v190, v121
	v_add_f32_e32 v37, v191, v137
	v_pk_mul_f32 v[188:189], v[34:35], v[36:37] op_sel:[0,1]
	s_nop 0
	v_pk_fma_f32 v[190:191], v[32:33], v[36:37], v[188:189] op_sel_hi:[1,0,1] neg_lo:[0,0,1]
	s_nop 0
	v_add_f32_e32 v36, v190, v122
	v_add_f32_e32 v37, v191, v138
	v_pk_mul_f32 v[188:189], v[34:35], v[36:37] op_sel:[0,1]
	s_nop 0
	v_pk_fma_f32 v[190:191], v[32:33], v[36:37], v[188:189] op_sel_hi:[1,0,1] neg_lo:[0,0,1]
	s_nop 0
	v_add_f32_e32 v36, v190, v123
	v_add_f32_e32 v37, v191, v139
	v_pk_mul_f32 v[188:189], v[34:35], v[36:37] op_sel:[0,1]
	s_nop 0
	v_pk_fma_f32 v[190:191], v[32:33], v[36:37], v[188:189] op_sel_hi:[1,0,1] neg_lo:[0,0,1]
	s_nop 0
	v_add_f32_e32 v36, v190, v158
	v_add_f32_e32 v37, v191, v174
	v_pk_mul_f32 v[188:189], v[34:35], v[36:37] op_sel:[0,1]
	s_nop 0
	v_pk_fma_f32 v[190:191], v[32:33], v[36:37], v[188:189] op_sel_hi:[1,0,1] neg_lo:[0,0,1]
	s_nop 0
	v_add_f32_e32 v36, v190, v159
	v_add_f32_e32 v37, v191, v175
	v_pk_mul_f32 v[188:189], v[34:35], v[36:37] op_sel:[0,1]
	s_nop 0
	v_pk_fma_f32 v[190:191], v[32:33], v[36:37], v[188:189] op_sel_hi:[1,0,1] neg_lo:[0,0,1]
	s_nop 0
	v_add_f32_e32 v36, v190, v160
	v_add_f32_e32 v37, v191, v176
	v_pk_mul_f32 v[188:189], v[34:35], v[36:37] op_sel:[0,1]
	s_nop 0
	v_pk_fma_f32 v[190:191], v[32:33], v[36:37], v[188:189] op_sel_hi:[1,0,1] neg_lo:[0,0,1]
	s_nop 0
	v_add_f32_e32 v36, v190, v161
	v_add_f32_e32 v37, v191, v177
	ds_read2_b32 v[178:179], v186 offset0:0 offset1:2
	ds_read2_b32 v[180:181], v186 offset0:4 offset1:6
	ds_read2_b32 v[182:183], v186 offset0:8 offset1:10
	ds_read2_b32 v[184:185], v186 offset0:12 offset1:14
	s_waitcnt lgkmcnt(0)
; __device__ __forceinline__ void s5_pass1(const Params& p, int layer, int task, char* sm) {
;     ...
;   for (int l = 0; l < 128; l++) S5_STEP(sU + l * 16)
	v_add_u32_e32 v186, 0x800, v186
	v_mfma_f32_32x32x2_f32 v[108:123], v178, v16, 0
	v_mfma_f32_32x32x2_f32 v[124:139], v178, v17, 0
	v_mfma_f32_32x32x2_f32 v[146:161], v178, v12, 0
	v_mfma_f32_32x32x2_f32 v[162:177], v178, v13, 0
	v_mfma_f32_32x32x2_f32 v[108:123], v179, v18, v[108:123]
	v_mfma_f32_32x32x2_f32 v[124:139], v179, v19, v[124:139]
	v_mfma_f32_32x32x2_f32 v[146:161], v179, v14, v[146:161]
	v_mfma_f32_32x32x2_f32 v[162:177], v179, v15, v[162:177]
	v_mfma_f32_32x32x2_f32 v[108:123], v180, v20, v[108:123]
	v_mfma_f32_32x32x2_f32 v[124:139], v180, v21, v[124:139]
	v_mfma_f32_32x32x2_f32 v[146:161], v180, v8, v[146:161]
	v_mfma_f32_32x32x2_f32 v[162:177], v180, v9, v[162:177]
	v_mfma_f32_32x32x2_f32 v[108:123], v181, v22, v[108:123]
	v_mfma_f32_32x32x2_f32 v[124:139], v181, v23, v[124:139]
	v_mfma_f32_32x32x2_f32 v[146:161], v181, v10, v[146:161]
	v_mfma_f32_32x32x2_f32 v[162:177], v181, v11, v[162:177]
	v_mfma_f32_32x32x2_f32 v[108:123], v182, v24, v[108:123]
	v_mfma_f32_32x32x2_f32 v[124:139], v182, v25, v[124:139]
	v_mfma_f32_32x32x2_f32 v[146:161], v182, v4, v[146:161]
	v_mfma_f32_32x32x2_f32 v[162:177], v182, v5, v[162:177]
	v_mfma_f32_32x32x2_f32 v[108:123], v183, v26, v[108:123]
	v_mfma_f32_32x32x2_f32 v[124:139], v183, v27, v[124:139]
	v_mfma_f32_32x32x2_f32 v[146:161], v183, v6, v[146:161]
	v_mfma_f32_32x32x2_f32 v[162:177], v183, v7, v[162:177]
	v_mfma_f32_32x32x2_f32 v[108:123], v184, v28, v[108:123]
	v_mfma_f32_32x32x2_f32 v[124:139], v184, v29, v[124:139]
	v_mfma_f32_32x32x2_f32 v[146:161], v184, v0, v[146:161]
	v_mfma_f32_32x32x2_f32 v[162:177], v184, v1, v[162:177]
	v_mfma_f32_32x32x2_f32 v[108:123], v185, v30, v[108:123]
	v_mfma_f32_32x32x2_f32 v[124:139], v185, v31, v[124:139]
	v_mfma_f32_32x32x2_f32 v[146:161], v185, v2, v[146:161]
	v_mfma_f32_32x32x2_f32 v[162:177], v185, v3, v[162:177]
	s_nop 7
	s_nop 7
	s_nop 7
	v_permlane32_swap_b32_e32 v108, v146
	v_permlane32_swap_b32_e32 v124, v162
	v_permlane32_swap_b32_e32 v109, v147
	v_permlane32_swap_b32_e32 v125, v163
	v_permlane32_swap_b32_e32 v110, v148
	v_permlane32_swap_b32_e32 v126, v164
	v_permlane32_swap_b32_e32 v111, v149
	v_permlane32_swap_b32_e32 v127, v165
	v_permlane32_swap_b32_e32 v112, v150
	v_permlane32_swap_b32_e32 v128, v166
	v_permlane32_swap_b32_e32 v113, v151
	v_permlane32_swap_b32_e32 v129, v167
	v_permlane32_swap_b32_e32 v114, v152
	v_permlane32_swap_b32_e32 v130, v168
	v_permlane32_swap_b32_e32 v115, v153
	v_permlane32_swap_b32_e32 v131, v169
	v_permlane32_swap_b32_e32 v116, v154
	v_permlane32_swap_b32_e32 v132, v170
	v_permlane32_swap_b32_e32 v117, v155
	v_permlane32_swap_b32_e32 v133, v171
	v_permlane32_swap_b32_e32 v118, v156
	v_permlane32_swap_b32_e32 v134, v172
	v_permlane32_swap_b32_e32 v119, v157
	v_permlane32_swap_b32_e32 v135, v173
	v_permlane32_swap_b32_e32 v120, v158
	v_permlane32_swap_b32_e32 v136, v174
	v_permlane32_swap_b32_e32 v121, v159
	v_permlane32_swap_b32_e32 v137, v175
	v_permlane32_swap_b32_e32 v122, v160
	v_permlane32_swap_b32_e32 v138, v176
	v_permlane32_swap_b32_e32 v123, v161
	v_permlane32_swap_b32_e32 v139, v177
	v_pk_mul_f32 v[188:189], v[34:35], v[36:37] op_sel:[0,1]
	s_nop 0
	v_pk_fma_f32 v[190:191], v[32:33], v[36:37], v[188:189] op_sel_hi:[1,0,1] neg_lo:[0,0,1]
	s_nop 0
	v_add_f32_e32 v36, v190, v108
	v_add_f32_e32 v37, v191, v124
	v_pk_mul_f32 v[188:189], v[34:35], v[36:37] op_sel:[0,1]
	s_nop 0
	v_pk_fma_f32 v[190:191], v[32:33], v[36:37], v[188:189] op_sel_hi:[1,0,1] neg_lo:[0,0,1]
	s_nop 0
	v_add_f32_e32 v36, v190, v109
	v_add_f32_e32 v37, v191, v125
	v_pk_mul_f32 v[188:189], v[34:35], v[36:37] op_sel:[0,1]
	s_nop 0
	v_pk_fma_f32 v[190:191], v[32:33], v[36:37], v[188:189] op_sel_hi:[1,0,1] neg_lo:[0,0,1]
	s_nop 0
	v_add_f32_e32 v36, v190, v110
	v_add_f32_e32 v37, v191, v126
	v_pk_mul_f32 v[188:189], v[34:35], v[36:37] op_sel:[0,1]
	s_nop 0
	v_pk_fma_f32 v[190:191], v[32:33], v[36:37], v[188:189] op_sel_hi:[1,0,1] neg_lo:[0,0,1]
	s_nop 0
	v_add_f32_e32 v36, v190, v111
	v_add_f32_e32 v37, v191, v127
	v_pk_mul_f32 v[188:189], v[34:35], v[36:37] op_sel:[0,1]
	s_nop 0
	v_pk_fma_f32 v[190:191], v[32:33], v[36:37], v[188:189] op_sel_hi:[1,0,1] neg_lo:[0,0,1]
	s_nop 0
	v_add_f32_e32 v36, v190, v146
	v_add_f32_e32 v37, v191, v162
	v_pk_mul_f32 v[188:189], v[34:35], v[36:37] op_sel:[0,1]
	s_nop 0
	v_pk_fma_f32 v[190:191], v[32:33], v[36:37], v[188:189] op_sel_hi:[1,0,1] neg_lo:[0,0,1]
	s_nop 0
	v_add_f32_e32 v36, v190, v147
	v_add_f32_e32 v37, v191, v163
	v_pk_mul_f32 v[188:189], v[34:35], v[36:37] op_sel:[0,1]
	s_nop 0
	v_pk_fma_f32 v[190:191], v[32:33], v[36:37], v[188:189] op_sel_hi:[1,0,1] neg_lo:[0,0,1]
	s_nop 0
	v_add_f32_e32 v36, v190, v148
	v_add_f32_e32 v37, v191, v164
	v_pk_mul_f32 v[188:189], v[34:35], v[36:37] op_sel:[0,1]
	s_nop 0
	v_pk_fma_f32 v[190:191], v[32:33], v[36:37], v[188:189] op_sel_hi:[1,0,1] neg_lo:[0,0,1]
	s_nop 0
	v_add_f32_e32 v36, v190, v149
	v_add_f32_e32 v37, v191, v165
	v_pk_mul_f32 v[188:189], v[34:35], v[36:37] op_sel:[0,1]
	s_nop 0
	v_pk_fma_f32 v[190:191], v[32:33], v[36:37], v[188:189] op_sel_hi:[1,0,1] neg_lo:[0,0,1]
	s_nop 0
	v_add_f32_e32 v36, v190, v112
	v_add_f32_e32 v37, v191, v128
	v_pk_mul_f32 v[188:189], v[34:35], v[36:37] op_sel:[0,1]
	s_nop 0
	v_pk_fma_f32 v[190:191], v[32:33], v[36:37], v[188:189] op_sel_hi:[1,0,1] neg_lo:[0,0,1]
	s_nop 0
	v_add_f32_e32 v36, v190, v113
	v_add_f32_e32 v37, v191, v129
	v_pk_mul_f32 v[188:189], v[34:35], v[36:37] op_sel:[0,1]
	s_nop 0
	v_pk_fma_f32 v[190:191], v[32:33], v[36:37], v[188:189] op_sel_hi:[1,0,1] neg_lo:[0,0,1]
	s_nop 0
	v_add_f32_e32 v36, v190, v114
	v_add_f32_e32 v37, v191, v130
	v_pk_mul_f32 v[188:189], v[34:35], v[36:37] op_sel:[0,1]
; __device__ __forceinline__ void s5_pass1(const Params& p, int layer, int task, char* sm) {
;     ...
;   for (int l = 0; l < 128; l++) S5_STEP(sU + l * 16)
	s_nop 0
	v_pk_fma_f32 v[190:191], v[32:33], v[36:37], v[188:189] op_sel_hi:[1,0,1] neg_lo:[0,0,1]
	s_nop 0
	v_add_f32_e32 v36, v190, v115
	v_add_f32_e32 v37, v191, v131
	v_pk_mul_f32 v[188:189], v[34:35], v[36:37] op_sel:[0,1]
	s_nop 0
	v_pk_fma_f32 v[190:191], v[32:33], v[36:37], v[188:189] op_sel_hi:[1,0,1] neg_lo:[0,0,1]
	s_nop 0
	v_add_f32_e32 v36, v190, v150
	v_add_f32_e32 v37, v191, v166
	v_pk_mul_f32 v[188:189], v[34:35], v[36:37] op_sel:[0,1]
	s_nop 0
	v_pk_fma_f32 v[190:191], v[32:33], v[36:37], v[188:189] op_sel_hi:[1,0,1] neg_lo:[0,0,1]
	s_nop 0
	v_add_f32_e32 v36, v190, v151
	v_add_f32_e32 v37, v191, v167
	v_pk_mul_f32 v[188:189], v[34:35], v[36:37] op_sel:[0,1]
	s_nop 0
	v_pk_fma_f32 v[190:191], v[32:33], v[36:37], v[188:189] op_sel_hi:[1,0,1] neg_lo:[0,0,1]
	s_nop 0
	v_add_f32_e32 v36, v190, v152
	v_add_f32_e32 v37, v191, v168
	v_pk_mul_f32 v[188:189], v[34:35], v[36:37] op_sel:[0,1]
	s_nop 0
	v_pk_fma_f32 v[190:191], v[32:33], v[36:37], v[188:189] op_sel_hi:[1,0,1] neg_lo:[0,0,1]
	s_nop 0
	v_add_f32_e32 v36, v190, v153
	v_add_f32_e32 v37, v191, v169
	v_pk_mul_f32 v[188:189], v[34:35], v[36:37] op_sel:[0,1]
	s_nop 0
	v_pk_fma_f32 v[190:191], v[32:33], v[36:37], v[188:189] op_sel_hi:[1,0,1] neg_lo:[0,0,1]
	s_nop 0
	v_add_f32_e32 v36, v190, v116
	v_add_f32_e32 v37, v191, v132
	v_pk_mul_f32 v[188:189], v[34:35], v[36:37] op_sel:[0,1]
	s_nop 0
	v_pk_fma_f32 v[190:191], v[32:33], v[36:37], v[188:189] op_sel_hi:[1,0,1] neg_lo:[0,0,1]
	s_nop 0
	v_add_f32_e32 v36, v190, v117
	v_add_f32_e32 v37, v191, v133
	v_pk_mul_f32 v[188:189], v[34:35], v[36:37] op_sel:[0,1]
	s_nop 0
	v_pk_fma_f32 v[190:191], v[32:33], v[36:37], v[188:189] op_sel_hi:[1,0,1] neg_lo:[0,0,1]
	s_nop 0
	v_add_f32_e32 v36, v190, v118
	v_add_f32_e32 v37, v191, v134
	v_pk_mul_f32 v[188:189], v[34:35], v[36:37] op_sel:[0,1]
	s_nop 0
	v_pk_fma_f32 v[190:191], v[32:33], v[36:37], v[188:189] op_sel_hi:[1,0,1] neg_lo:[0,0,1]
	s_nop 0
	v_add_f32_e32 v36, v190, v119
	v_add_f32_e32 v37, v191, v135
	v_pk_mul_f32 v[188:189], v[34:35], v[36:37] op_sel:[0,1]
	s_nop 0
	v_pk_fma_f32 v[190:191], v[32:33], v[36:37], v[188:189] op_sel_hi:[1,0,1] neg_lo:[0,0,1]
	s_nop 0
	v_add_f32_e32 v36, v190, v154
	v_add_f32_e32 v37, v191, v170
	v_pk_mul_f32 v[188:189], v[34:35], v[36:37] op_sel:[0,1]
	s_nop 0
	v_pk_fma_f32 v[190:191], v[32:33], v[36:37], v[188:189] op_sel_hi:[1,0,1] neg_lo:[0,0,1]
	s_nop 0
	v_add_f32_e32 v36, v190, v155
	v_add_f32_e32 v37, v191, v171
	v_pk_mul_f32 v[188:189], v[34:35], v[36:37] op_sel:[0,1]
	s_nop 0
	v_pk_fma_f32 v[190:191], v[32:33], v[36:37], v[188:189] op_sel_hi:[1,0,1] neg_lo:[0,0,1]
	s_nop 0
	v_add_f32_e32 v36, v190, v156
	v_add_f32_e32 v37, v191, v172
	v_pk_mul_f32 v[188:189], v[34:35], v[36:37] op_sel:[0,1]
	s_nop 0
	v_pk_fma_f32 v[190:191], v[32:33], v[36:37], v[188:189] op_sel_hi:[1,0,1] neg_lo:[0,0,1]
	s_nop 0
	v_add_f32_e32 v36, v190, v157
	v_add_f32_e32 v37, v191, v173
	v_pk_mul_f32 v[188:189], v[34:35], v[36:37] op_sel:[0,1]
	s_nop 0
	v_pk_fma_f32 v[190:191], v[32:33], v[36:37], v[188:189] op_sel_hi:[1,0,1] neg_lo:[0,0,1]
	s_nop 0
	v_add_f32_e32 v36, v190, v120
	v_add_f32_e32 v37, v191, v136
	v_pk_mul_f32 v[188:189], v[34:35], v[36:37] op_sel:[0,1]
	s_nop 0
	v_pk_fma_f32 v[190:191], v[32:33], v[36:37], v[188:189] op_sel_hi:[1,0,1] neg_lo:[0,0,1]
	s_nop 0
	v_add_f32_e32 v36, v190, v121
	v_add_f32_e32 v37, v191, v137
	v_pk_mul_f32 v[188:189], v[34:35], v[36:37] op_sel:[0,1]
	s_nop 0
	v_pk_fma_f32 v[190:191], v[32:33], v[36:37], v[188:189] op_sel_hi:[1,0,1] neg_lo:[0,0,1]
	s_nop 0
	v_add_f32_e32 v36, v190, v122
	v_add_f32_e32 v37, v191, v138
	v_pk_mul_f32 v[188:189], v[34:35], v[36:37] op_sel:[0,1]
	s_nop 0
	v_pk_fma_f32 v[190:191], v[32:33], v[36:37], v[188:189] op_sel_hi:[1,0,1] neg_lo:[0,0,1]
	s_nop 0
	v_add_f32_e32 v36, v190, v123
	v_add_f32_e32 v37, v191, v139
	v_pk_mul_f32 v[188:189], v[34:35], v[36:37] op_sel:[0,1]
	s_nop 0
	v_pk_fma_f32 v[190:191], v[32:33], v[36:37], v[188:189] op_sel_hi:[1,0,1] neg_lo:[0,0,1]
	s_nop 0
	v_add_f32_e32 v36, v190, v158
	v_add_f32_e32 v37, v191, v174
	v_pk_mul_f32 v[188:189], v[34:35], v[36:37] op_sel:[0,1]
	s_nop 0
	v_pk_fma_f32 v[190:191], v[32:33], v[36:37], v[188:189] op_sel_hi:[1,0,1] neg_lo:[0,0,1]
	s_nop 0
	v_add_f32_e32 v36, v190, v159
	v_add_f32_e32 v37, v191, v175
	v_pk_mul_f32 v[188:189], v[34:35], v[36:37] op_sel:[0,1]
	s_nop 0
	v_pk_fma_f32 v[190:191], v[32:33], v[36:37], v[188:189] op_sel_hi:[1,0,1] neg_lo:[0,0,1]
	s_nop 0
	v_add_f32_e32 v36, v190, v160
	v_add_f32_e32 v37, v191, v176
	v_pk_mul_f32 v[188:189], v[34:35], v[36:37] op_sel:[0,1]
	s_nop 0
	v_pk_fma_f32 v[190:191], v[32:33], v[36:37], v[188:189] op_sel_hi:[1,0,1] neg_lo:[0,0,1]
	s_nop 0
	v_add_f32_e32 v36, v190, v161
	v_add_f32_e32 v37, v191, v177
	ds_read2_b32 v[178:179], v186 offset0:0 offset1:2
	ds_read2_b32 v[180:181], v186 offset0:4 offset1:6
	ds_read2_b32 v[182:183], v186 offset0:8 offset1:10
	ds_read2_b32 v[184:185], v186 offset0:12 offset1:14
	s_waitcnt lgkmcnt(0)
; __device__ __forceinline__ void s5_pass1(const Params& p, int layer, int task, char* sm) {
;     ...
;   for (int l = 0; l < 128; l++) S5_STEP(sU + l * 16)
	v_mfma_f32_32x32x2_f32 v[108:123], v178, v16, 0
	v_mfma_f32_32x32x2_f32 v[124:139], v178, v17, 0
	v_mfma_f32_32x32x2_f32 v[146:161], v178, v12, 0
	v_mfma_f32_32x32x2_f32 v[162:177], v178, v13, 0
	v_mfma_f32_32x32x2_f32 v[108:123], v179, v18, v[108:123]
	v_mfma_f32_32x32x2_f32 v[124:139], v179, v19, v[124:139]
	v_mfma_f32_32x32x2_f32 v[146:161], v179, v14, v[146:161]
	v_mfma_f32_32x32x2_f32 v[162:177], v179, v15, v[162:177]
	v_mfma_f32_32x32x2_f32 v[108:123], v180, v20, v[108:123]
	v_mfma_f32_32x32x2_f32 v[124:139], v180, v21, v[124:139]
	v_mfma_f32_32x32x2_f32 v[146:161], v180, v8, v[146:161]
	v_mfma_f32_32x32x2_f32 v[162:177], v180, v9, v[162:177]
	v_mfma_f32_32x32x2_f32 v[108:123], v181, v22, v[108:123]
	v_mfma_f32_32x32x2_f32 v[124:139], v181, v23, v[124:139]
	v_mfma_f32_32x32x2_f32 v[146:161], v181, v10, v[146:161]
	v_mfma_f32_32x32x2_f32 v[162:177], v181, v11, v[162:177]
	v_mfma_f32_32x32x2_f32 v[108:123], v182, v24, v[108:123]
	v_mfma_f32_32x32x2_f32 v[124:139], v182, v25, v[124:139]
	v_mfma_f32_32x32x2_f32 v[146:161], v182, v4, v[146:161]
	v_mfma_f32_32x32x2_f32 v[162:177], v182, v5, v[162:177]
	v_mfma_f32_32x32x2_f32 v[108:123], v183, v26, v[108:123]
	v_mfma_f32_32x32x2_f32 v[124:139], v183, v27, v[124:139]
	v_mfma_f32_32x32x2_f32 v[146:161], v183, v6, v[146:161]
	v_mfma_f32_32x32x2_f32 v[162:177], v183, v7, v[162:177]
	v_mfma_f32_32x32x2_f32 v[108:123], v184, v28, v[108:123]
	v_mfma_f32_32x32x2_f32 v[124:139], v184, v29, v[124:139]
	v_mfma_f32_32x32x2_f32 v[146:161], v184, v0, v[146:161]
	v_mfma_f32_32x32x2_f32 v[162:177], v184, v1, v[162:177]
	v_mfma_f32_32x32x2_f32 v[108:123], v185, v30, v[108:123]
	v_mfma_f32_32x32x2_f32 v[124:139], v185, v31, v[124:139]
	v_mfma_f32_32x32x2_f32 v[146:161], v185, v2, v[146:161]
	v_mfma_f32_32x32x2_f32 v[162:177], v185, v3, v[162:177]
	s_nop 7
	s_nop 7
	s_nop 7
	v_permlane32_swap_b32_e32 v108, v146
	v_permlane32_swap_b32_e32 v124, v162
	v_permlane32_swap_b32_e32 v109, v147
	v_permlane32_swap_b32_e32 v125, v163
	v_permlane32_swap_b32_e32 v110, v148
	v_permlane32_swap_b32_e32 v126, v164
	v_permlane32_swap_b32_e32 v111, v149
	v_permlane32_swap_b32_e32 v127, v165
	v_permlane32_swap_b32_e32 v112, v150
	v_permlane32_swap_b32_e32 v128, v166
	v_permlane32_swap_b32_e32 v113, v151
	v_permlane32_swap_b32_e32 v129, v167
	v_permlane32_swap_b32_e32 v114, v152
	v_permlane32_swap_b32_e32 v130, v168
	v_permlane32_swap_b32_e32 v115, v153
	v_permlane32_swap_b32_e32 v131, v169
	v_permlane32_swap_b32_e32 v116, v154
	v_permlane32_swap_b32_e32 v132, v170
	v_permlane32_swap_b32_e32 v117, v155
	v_permlane32_swap_b32_e32 v133, v171
	v_permlane32_swap_b32_e32 v118, v156
	v_permlane32_swap_b32_e32 v134, v172
	v_permlane32_swap_b32_e32 v119, v157
	v_permlane32_swap_b32_e32 v135, v173
	v_permlane32_swap_b32_e32 v120, v158
	v_permlane32_swap_b32_e32 v136, v174
	v_permlane32_swap_b32_e32 v121, v159
	v_permlane32_swap_b32_e32 v137, v175
	v_permlane32_swap_b32_e32 v122, v160
	v_permlane32_swap_b32_e32 v138, v176
	v_permlane32_swap_b32_e32 v123, v161
	v_permlane32_swap_b32_e32 v139, v177
	v_pk_mul_f32 v[188:189], v[34:35], v[36:37] op_sel:[0,1]
	s_nop 0
	v_pk_fma_f32 v[190:191], v[32:33], v[36:37], v[188:189] op_sel_hi:[1,0,1] neg_lo:[0,0,1]
	s_nop 0
	v_add_f32_e32 v36, v190, v108
	v_add_f32_e32 v37, v191, v124
	v_pk_mul_f32 v[188:189], v[34:35], v[36:37] op_sel:[0,1]
	s_nop 0
	v_pk_fma_f32 v[190:191], v[32:33], v[36:37], v[188:189] op_sel_hi:[1,0,1] neg_lo:[0,0,1]
	s_nop 0
	v_add_f32_e32 v36, v190, v109
	v_add_f32_e32 v37, v191, v125
	v_pk_mul_f32 v[188:189], v[34:35], v[36:37] op_sel:[0,1]
	s_nop 0
	v_pk_fma_f32 v[190:191], v[32:33], v[36:37], v[188:189] op_sel_hi:[1,0,1] neg_lo:[0,0,1]
	s_nop 0
	v_add_f32_e32 v36, v190, v110
	v_add_f32_e32 v37, v191, v126
	v_pk_mul_f32 v[188:189], v[34:35], v[36:37] op_sel:[0,1]
	s_nop 0
	v_pk_fma_f32 v[190:191], v[32:33], v[36:37], v[188:189] op_sel_hi:[1,0,1] neg_lo:[0,0,1]
	s_nop 0
	v_add_f32_e32 v36, v190, v111
	v_add_f32_e32 v37, v191, v127
	v_pk_mul_f32 v[188:189], v[34:35], v[36:37] op_sel:[0,1]
	s_nop 0
	v_pk_fma_f32 v[190:191], v[32:33], v[36:37], v[188:189] op_sel_hi:[1,0,1] neg_lo:[0,0,1]
	s_nop 0
	v_add_f32_e32 v36, v190, v146
	v_add_f32_e32 v37, v191, v162
	v_pk_mul_f32 v[188:189], v[34:35], v[36:37] op_sel:[0,1]
	s_nop 0
	v_pk_fma_f32 v[190:191], v[32:33], v[36:37], v[188:189] op_sel_hi:[1,0,1] neg_lo:[0,0,1]
	s_nop 0
	v_add_f32_e32 v36, v190, v147
	v_add_f32_e32 v37, v191, v163
	v_pk_mul_f32 v[188:189], v[34:35], v[36:37] op_sel:[0,1]
	s_nop 0
	v_pk_fma_f32 v[190:191], v[32:33], v[36:37], v[188:189] op_sel_hi:[1,0,1] neg_lo:[0,0,1]
	s_nop 0
	v_add_f32_e32 v36, v190, v148
	v_add_f32_e32 v37, v191, v164
	v_pk_mul_f32 v[188:189], v[34:35], v[36:37] op_sel:[0,1]
	s_nop 0
	v_pk_fma_f32 v[190:191], v[32:33], v[36:37], v[188:189] op_sel_hi:[1,0,1] neg_lo:[0,0,1]
	s_nop 0
	v_add_f32_e32 v36, v190, v149
	v_add_f32_e32 v37, v191, v165
	v_pk_mul_f32 v[188:189], v[34:35], v[36:37] op_sel:[0,1]
	s_nop 0
	v_pk_fma_f32 v[190:191], v[32:33], v[36:37], v[188:189] op_sel_hi:[1,0,1] neg_lo:[0,0,1]
	s_nop 0
	v_add_f32_e32 v36, v190, v112
	v_add_f32_e32 v37, v191, v128
	v_pk_mul_f32 v[188:189], v[34:35], v[36:37] op_sel:[0,1]
	s_nop 0
	v_pk_fma_f32 v[190:191], v[32:33], v[36:37], v[188:189] op_sel_hi:[1,0,1] neg_lo:[0,0,1]
	s_nop 0
	v_add_f32_e32 v36, v190, v113
	v_add_f32_e32 v37, v191, v129
	v_pk_mul_f32 v[188:189], v[34:35], v[36:37] op_sel:[0,1]
	s_nop 0
; __device__ __forceinline__ void s5_pass1(const Params& p, int layer, int task, char* sm) {
;     ...
;   for (int l = 0; l < 128; l++) S5_STEP(sU + l * 16)
;   *(float2*)(p.END + (((size_t)(b * 128 + c) * 32 + g) * 64 + lane) * 2) = make_float2(sr, si);
	v_pk_fma_f32 v[190:191], v[32:33], v[36:37], v[188:189] op_sel_hi:[1,0,1] neg_lo:[0,0,1]
	s_nop 0
	v_add_f32_e32 v36, v190, v114
	v_add_f32_e32 v37, v191, v130
	v_pk_mul_f32 v[188:189], v[34:35], v[36:37] op_sel:[0,1]
	s_nop 0
	v_pk_fma_f32 v[190:191], v[32:33], v[36:37], v[188:189] op_sel_hi:[1,0,1] neg_lo:[0,0,1]
	s_nop 0
	v_add_f32_e32 v36, v190, v115
	v_add_f32_e32 v37, v191, v131
	v_pk_mul_f32 v[188:189], v[34:35], v[36:37] op_sel:[0,1]
	s_nop 0
	v_pk_fma_f32 v[190:191], v[32:33], v[36:37], v[188:189] op_sel_hi:[1,0,1] neg_lo:[0,0,1]
	s_nop 0
	v_add_f32_e32 v36, v190, v150
	v_add_f32_e32 v37, v191, v166
	v_pk_mul_f32 v[188:189], v[34:35], v[36:37] op_sel:[0,1]
	s_nop 0
	v_pk_fma_f32 v[190:191], v[32:33], v[36:37], v[188:189] op_sel_hi:[1,0,1] neg_lo:[0,0,1]
	s_nop 0
	v_add_f32_e32 v36, v190, v151
	v_add_f32_e32 v37, v191, v167
	v_pk_mul_f32 v[188:189], v[34:35], v[36:37] op_sel:[0,1]
	s_nop 0
	v_pk_fma_f32 v[190:191], v[32:33], v[36:37], v[188:189] op_sel_hi:[1,0,1] neg_lo:[0,0,1]
	s_nop 0
	v_add_f32_e32 v36, v190, v152
	v_add_f32_e32 v37, v191, v168
	v_pk_mul_f32 v[188:189], v[34:35], v[36:37] op_sel:[0,1]
	s_nop 0
	v_pk_fma_f32 v[190:191], v[32:33], v[36:37], v[188:189] op_sel_hi:[1,0,1] neg_lo:[0,0,1]
	s_nop 0
	v_add_f32_e32 v36, v190, v153
	v_add_f32_e32 v37, v191, v169
	v_pk_mul_f32 v[188:189], v[34:35], v[36:37] op_sel:[0,1]
	s_nop 0
	v_pk_fma_f32 v[190:191], v[32:33], v[36:37], v[188:189] op_sel_hi:[1,0,1] neg_lo:[0,0,1]
	s_nop 0
	v_add_f32_e32 v36, v190, v116
	v_add_f32_e32 v37, v191, v132
	v_pk_mul_f32 v[188:189], v[34:35], v[36:37] op_sel:[0,1]
	s_nop 0
	v_pk_fma_f32 v[190:191], v[32:33], v[36:37], v[188:189] op_sel_hi:[1,0,1] neg_lo:[0,0,1]
	s_nop 0
	v_add_f32_e32 v36, v190, v117
	v_add_f32_e32 v37, v191, v133
	v_pk_mul_f32 v[188:189], v[34:35], v[36:37] op_sel:[0,1]
	s_nop 0
	v_pk_fma_f32 v[190:191], v[32:33], v[36:37], v[188:189] op_sel_hi:[1,0,1] neg_lo:[0,0,1]
	s_nop 0
	v_add_f32_e32 v36, v190, v118
	v_add_f32_e32 v37, v191, v134
	v_pk_mul_f32 v[188:189], v[34:35], v[36:37] op_sel:[0,1]
	s_nop 0
	v_pk_fma_f32 v[190:191], v[32:33], v[36:37], v[188:189] op_sel_hi:[1,0,1] neg_lo:[0,0,1]
	s_nop 0
	v_add_f32_e32 v36, v190, v119
	v_add_f32_e32 v37, v191, v135
	v_pk_mul_f32 v[188:189], v[34:35], v[36:37] op_sel:[0,1]
	s_nop 0
	v_pk_fma_f32 v[190:191], v[32:33], v[36:37], v[188:189] op_sel_hi:[1,0,1] neg_lo:[0,0,1]
	s_nop 0
	v_add_f32_e32 v36, v190, v154
	v_add_f32_e32 v37, v191, v170
	v_pk_mul_f32 v[188:189], v[34:35], v[36:37] op_sel:[0,1]
	s_nop 0
	v_pk_fma_f32 v[190:191], v[32:33], v[36:37], v[188:189] op_sel_hi:[1,0,1] neg_lo:[0,0,1]
	s_nop 0
	v_add_f32_e32 v36, v190, v155
	v_add_f32_e32 v37, v191, v171
	v_pk_mul_f32 v[188:189], v[34:35], v[36:37] op_sel:[0,1]
	s_nop 0
	v_pk_fma_f32 v[190:191], v[32:33], v[36:37], v[188:189] op_sel_hi:[1,0,1] neg_lo:[0,0,1]
	s_nop 0
	v_add_f32_e32 v36, v190, v156
	v_add_f32_e32 v37, v191, v172
	v_pk_mul_f32 v[188:189], v[34:35], v[36:37] op_sel:[0,1]
	s_nop 0
	v_pk_fma_f32 v[190:191], v[32:33], v[36:37], v[188:189] op_sel_hi:[1,0,1] neg_lo:[0,0,1]
	s_nop 0
	v_add_f32_e32 v36, v190, v157
	v_add_f32_e32 v37, v191, v173
	v_pk_mul_f32 v[188:189], v[34:35], v[36:37] op_sel:[0,1]
	s_nop 0
	v_pk_fma_f32 v[190:191], v[32:33], v[36:37], v[188:189] op_sel_hi:[1,0,1] neg_lo:[0,0,1]
	s_nop 0
	v_add_f32_e32 v36, v190, v120
	v_add_f32_e32 v37, v191, v136
	v_pk_mul_f32 v[188:189], v[34:35], v[36:37] op_sel:[0,1]
	s_nop 0
	v_pk_fma_f32 v[190:191], v[32:33], v[36:37], v[188:189] op_sel_hi:[1,0,1] neg_lo:[0,0,1]
	s_nop 0
	v_add_f32_e32 v36, v190, v121
	v_add_f32_e32 v37, v191, v137
	v_pk_mul_f32 v[188:189], v[34:35], v[36:37] op_sel:[0,1]
	s_nop 0
	v_pk_fma_f32 v[190:191], v[32:33], v[36:37], v[188:189] op_sel_hi:[1,0,1] neg_lo:[0,0,1]
	s_nop 0
	v_add_f32_e32 v36, v190, v122
	v_add_f32_e32 v37, v191, v138
	v_pk_mul_f32 v[188:189], v[34:35], v[36:37] op_sel:[0,1]
	s_nop 0
	v_pk_fma_f32 v[190:191], v[32:33], v[36:37], v[188:189] op_sel_hi:[1,0,1] neg_lo:[0,0,1]
	s_nop 0
	v_add_f32_e32 v36, v190, v123
	v_add_f32_e32 v37, v191, v139
	v_pk_mul_f32 v[188:189], v[34:35], v[36:37] op_sel:[0,1]
	s_nop 0
	v_pk_fma_f32 v[190:191], v[32:33], v[36:37], v[188:189] op_sel_hi:[1,0,1] neg_lo:[0,0,1]
	s_nop 0
	v_add_f32_e32 v36, v190, v158
	v_add_f32_e32 v37, v191, v174
	v_pk_mul_f32 v[188:189], v[34:35], v[36:37] op_sel:[0,1]
	s_nop 0
	v_pk_fma_f32 v[190:191], v[32:33], v[36:37], v[188:189] op_sel_hi:[1,0,1] neg_lo:[0,0,1]
	s_nop 0
	v_add_f32_e32 v36, v190, v159
	v_add_f32_e32 v37, v191, v175
	v_pk_mul_f32 v[188:189], v[34:35], v[36:37] op_sel:[0,1]
	s_nop 0
	v_pk_fma_f32 v[190:191], v[32:33], v[36:37], v[188:189] op_sel_hi:[1,0,1] neg_lo:[0,0,1]
	s_nop 0
	v_add_f32_e32 v36, v190, v160
	v_add_f32_e32 v37, v191, v176
	v_pk_mul_f32 v[188:189], v[34:35], v[36:37] op_sel:[0,1]
	s_nop 0
	v_pk_fma_f32 v[190:191], v[32:33], v[36:37], v[188:189] op_sel_hi:[1,0,1] neg_lo:[0,0,1]
	s_nop 0
	v_add_f32_e32 v36, v190, v161
	v_add_f32_e32 v37, v191, v177
	v_mov_b32_e32 v38, v37
	s_lshl_b32 s1, s1, 12
	s_lshl_b32 s0, s0, 5
	s_or_b32 s0, s0, s1
	v_or_b32_e32 v0, s0, v40
	v_lshlrev_b32_e32 v1, 1, v39
	v_readlane_b32 s0, v253, 38
	v_lshl_or_b32 v144, v0, 7, v1
	v_readlane_b32 s1, v253, 39
	v_readlane_b32 s2, v253, 40
	v_readlane_b32 s3, v253, 41
	v_lshl_add_u64 v[0:1], v[144:145], 2, s[0:1]
	v_readlane_b32 s4, v253, 42
	v_readlane_b32 s5, v253, 43
	v_readlane_b32 s6, v253, 44
	v_readlane_b32 s7, v253, 45
	global_store_dwordx2 v[0:1], v[36:37], off
